# P6 epilogue: x residual loads 4-step pipelined, fw loads hoisted, no store-drain waits
# baseline (speedup 1.0000x reference)
.LBB0_923:
	s_barrier
	s_lshl_b32 s1, s18, 8
	v_readfirstlane_b32 s7, v0
	s_ashr_i32 s2, s7, 6
	s_and_b32 s0, s2, 3
	s_lshl_b32 s3, s0, 5
	s_or_b32 s1, s3, s1
	v_lshrrev_b32_e32 v130, 2, v0
	v_and_or_b32 v130, v130, 12, s1
	v_mov_b32_e32 v147, 0
	v_lshlrev_b32_e32 v146, 2, v130
	v_lshl_add_u64 v[130:131], s[82:83], 0, v[146:147]
	s_mov_b64 s[4:5], 0xb40000
	v_lshl_add_u64 v[142:143], v[130:131], 0, s[4:5]
	v_and_b32_e32 v167, 15, v0
	s_ashr_i32 s4, s7, 8
	v_lshl_or_b32 v166, s4, 6, v167
	s_lshl_b32 s3, s6, 8
	v_add_u32_e32 v148, s3, v166
	v_readlane_b32 s36, v254, 8
	v_ashrrev_i32_e32 v149, 31, v148
	v_readlane_b32 s37, v254, 9
	s_mov_b32 s1, 0xb40000
	v_lshlrev_b64 v[134:135], 12, v[148:149]
	s_mov_b64 s[12:13], s[36:37]
	v_add_co_u32_e32 v130, vcc, s1, v130
	v_lshl_add_u64 v[134:135], s[12:13], 0, v[134:135]
	s_nop 0
	v_addc_co_u32_e32 v131, vcc, 0, v131, vcc
	v_lshl_add_u64 v[144:145], v[134:135], 0, v[146:147]
	global_load_dwordx4 v[130:133], v[130:131], off
	global_load_dwordx4 v[138:141], v[142:143], off offset:64
	global_load_dwordx4 v[134:137], v[142:143], off offset:512
	v_lshl_add_u32 v250, v148, 12, v146
	global_load_dwordx4 v[142:145], v[142:143], off offset:576
	global_load_dwordx4 v[202:205], v250, s[12:13]
	global_load_dwordx4 v[206:209], v250, s[12:13] offset:64
	global_load_dwordx4 v[210:213], v250, s[12:13] offset:512
	global_load_dwordx4 v[214:217], v250, s[12:13] offset:576
	v_add_u32_e32 v251, 0x10000, v250
	global_load_dwordx4 v[218:221], v251, s[12:13]
	global_load_dwordx4 v[222:225], v251, s[12:13] offset:64
	global_load_dwordx4 v[226:229], v251, s[12:13] offset:512
	global_load_dwordx4 v[230:233], v251, s[12:13] offset:576
	v_add_u32_e32 v252, 0x20000, v250
	global_load_dwordx4 v[234:237], v252, s[12:13]
	global_load_dwordx4 v[238:241], v252, s[12:13] offset:64
	global_load_dwordx4 v[242:245], v252, s[12:13] offset:512
	global_load_dwordx4 v[246:249], v252, s[12:13] offset:576
	v_add_u32_e32 v253, 0x30000, v250
	global_load_dwordx4 v[172:175], v253, s[12:13]
	global_load_dwordx4 v[176:179], v253, s[12:13] offset:64
	global_load_dwordx4 v[180:183], v253, s[12:13] offset:512
	global_load_dwordx4 v[184:187], v253, s[12:13] offset:576
	v_or_b32_e32 v150, 16, v148
	v_ashrrev_i32_e32 v151, 31, v150
	v_mbcnt_hi_u32_b32 v198, -1, v1
	v_xor_b32_e32 v1, 16, v198
	s_lshl_b32 s0, s0, 3
	s_add_i32 s5, s0, 0
	v_readlane_b32 s38, v254, 10
	v_readlane_b32 s39, v254, 11
	v_readlane_b32 s40, v254, 12
	v_readlane_b32 s41, v254, 13
	v_readlane_b32 s42, v254, 14
	v_readlane_b32 s43, v254, 15
	v_readlane_b32 s44, v254, 16
	v_readlane_b32 s45, v254, 17
	v_readlane_b32 s46, v254, 18
	v_readlane_b32 s47, v254, 19
	v_readlane_b32 s48, v254, 20
	v_readlane_b32 s49, v254, 21
	v_readlane_b32 s50, v254, 22
	v_readlane_b32 s51, v254, 23
	s_waitcnt vmcnt(12)
	v_pk_fma_f32 v[68:69], v[68:69], v[132:133], v[204:205]
	v_pk_fma_f32 v[66:67], v[66:67], v[130:131], v[202:203]
	v_pk_fma_f32 v[40:41], v[40:41], v[140:141], v[208:209]
	v_pk_fma_f32 v[38:39], v[38:39], v[138:139], v[206:207]
	v_pk_fma_f32 v[16:17], v[16:17], v[136:137], v[212:213]
	v_pk_fma_f32 v[14:15], v[14:15], v[134:135], v[210:211]
	v_pk_fma_f32 v[4:5], v[4:5], v[144:145], v[216:217]
	v_pk_fma_f32 v[2:3], v[2:3], v[142:143], v[214:215]
	v_add_u32_e32 v251, 0x80000, v250
	global_load_dwordx4 v[202:205], v251, s[12:13]
	global_load_dwordx4 v[206:209], v251, s[12:13] offset:64
	global_load_dwordx4 v[210:213], v251, s[12:13] offset:512
	global_load_dwordx4 v[214:217], v251, s[12:13] offset:576
	v_or_b32_e32 v152, 32, v148
	v_ashrrev_i32_e32 v153, 31, v152
	v_mov_b32_e32 v188, v67
	v_mov_b32_e32 v189, v68
	v_mov_b32_e32 v190, v66
	v_mov_b32_e32 v191, v69
	v_mov_b32_e32 v192, v39
	v_mov_b32_e32 v193, v40
	v_pk_add_f32 v[188:189], v[188:189], v[190:191]
	v_add_f32_e32 v195, v16, v17
	v_mov_b32_e32 v194, v3
	v_mov_b32_e32 v196, v5
	s_waitcnt vmcnt(12)
	v_pk_fma_f32 v[80:81], v[80:81], v[132:133], v[220:221]
	v_pk_fma_f32 v[78:79], v[78:79], v[130:131], v[218:219]
	v_pk_fma_f32 v[48:49], v[48:49], v[140:141], v[224:225]
	v_pk_fma_f32 v[46:47], v[46:47], v[138:139], v[222:223]
	v_pk_fma_f32 v[24:25], v[24:25], v[136:137], v[228:229]
	v_pk_fma_f32 v[22:23], v[22:23], v[134:135], v[226:227]
	v_pk_fma_f32 v[8:9], v[8:9], v[144:145], v[232:233]
	v_pk_fma_f32 v[6:7], v[6:7], v[142:143], v[230:231]
	v_add_u32_e32 v251, 0x90000, v250
	global_load_dwordx4 v[218:221], v251, s[12:13]
	global_load_dwordx4 v[222:225], v251, s[12:13] offset:64
	global_load_dwordx4 v[226:229], v251, s[12:13] offset:512
	global_load_dwordx4 v[230:233], v251, s[12:13] offset:576
	v_or_b32_e32 v154, 48, v148
	v_ashrrev_i32_e32 v155, 31, v154
	s_waitcnt vmcnt(12)
	v_pk_fma_f32 v[92:93], v[92:93], v[132:133], v[236:237]
	v_pk_fma_f32 v[90:91], v[90:91], v[130:131], v[234:235]
	v_pk_fma_f32 v[60:61], v[60:61], v[140:141], v[240:241]
	v_pk_fma_f32 v[58:59], v[58:59], v[138:139], v[238:239]
	v_pk_fma_f32 v[32:33], v[32:33], v[136:137], v[244:245]
	v_pk_fma_f32 v[30:31], v[30:31], v[134:135], v[242:243]
	v_pk_fma_f32 v[12:13], v[12:13], v[144:145], v[248:249]
	v_pk_fma_f32 v[10:11], v[10:11], v[142:143], v[246:247]
	v_add_u32_e32 v251, 0xa0000, v250
	global_load_dwordx4 v[234:237], v251, s[12:13]
	global_load_dwordx4 v[238:241], v251, s[12:13] offset:64
	global_load_dwordx4 v[242:245], v251, s[12:13] offset:512
	global_load_dwordx4 v[246:249], v251, s[12:13] offset:576
	v_add_u32_e32 v156, 0x80, v148
	v_ashrrev_i32_e32 v157, 31, v156
	s_waitcnt vmcnt(12)
	v_pk_fma_f32 v[104:105], v[104:105], v[132:133], v[174:175]
	v_pk_fma_f32 v[102:103], v[102:103], v[130:131], v[172:173]
	v_pk_fma_f32 v[72:73], v[72:73], v[140:141], v[178:179]
	v_pk_fma_f32 v[70:71], v[70:71], v[138:139], v[176:177]
	v_pk_fma_f32 v[44:45], v[44:45], v[136:137], v[182:183]
	v_pk_fma_f32 v[42:43], v[42:43], v[134:135], v[180:181]
	v_pk_fma_f32 v[20:21], v[20:21], v[144:145], v[186:187]
	v_pk_fma_f32 v[18:19], v[18:19], v[142:143], v[184:185]
	v_add_u32_e32 v251, 0xb0000, v250
	global_load_dwordx4 v[172:175], v251, s[12:13]
	global_load_dwordx4 v[176:179], v251, s[12:13] offset:64
	global_load_dwordx4 v[180:183], v251, s[12:13] offset:512
	global_load_dwordx4 v[184:187], v251, s[12:13] offset:576
	v_add_u32_e32 v158, 0x90, v148
	v_ashrrev_i32_e32 v159, 31, v158
	s_waitcnt vmcnt(12)
	v_pk_fma_f32 v[108:109], v[108:109], v[132:133], v[204:205]
	v_pk_fma_f32 v[106:107], v[106:107], v[130:131], v[202:203]
	v_pk_fma_f32 v[84:85], v[84:85], v[140:141], v[208:209]
	v_pk_fma_f32 v[82:83], v[82:83], v[138:139], v[206:207]
	v_pk_fma_f32 v[52:53], v[52:53], v[136:137], v[212:213]
	v_pk_fma_f32 v[50:51], v[50:51], v[134:135], v[210:211]
	v_pk_fma_f32 v[28:29], v[28:29], v[144:145], v[216:217]
	v_pk_fma_f32 v[26:27], v[26:27], v[142:143], v[214:215]
	v_add_u32_e32 v160, 0xa0, v148
	v_ashrrev_i32_e32 v161, 31, v160
	s_waitcnt vmcnt(8)
	v_pk_fma_f32 v[120:121], v[120:121], v[132:133], v[220:221]
	v_pk_fma_f32 v[118:119], v[118:119], v[130:131], v[218:219]
	v_pk_fma_f32 v[96:97], v[96:97], v[140:141], v[224:225]
	v_pk_fma_f32 v[94:95], v[94:95], v[138:139], v[222:223]
	v_pk_fma_f32 v[64:65], v[64:65], v[136:137], v[228:229]
	v_pk_fma_f32 v[62:63], v[62:63], v[134:135], v[226:227]
	v_pk_fma_f32 v[36:37], v[36:37], v[144:145], v[232:233]
	v_pk_fma_f32 v[34:35], v[34:35], v[142:143], v[230:231]
	s_nop 0
	v_and_b32_e32 v162, 64, v198
	v_add_u32_e32 v199, 64, v162
	v_add_u32_e32 v162, 0xb0, v148
	v_ashrrev_i32_e32 v163, 31, v162
	v_add_f32_e32 v147, v188, v189
	v_add_f32_e32 v197, 0, v147
	v_cmp_lt_i32_e32 vcc, v1, v199
	s_waitcnt vmcnt(4)
	v_pk_fma_f32 v[128:129], v[128:129], v[132:133], v[236:237]
	v_pk_fma_f32 v[126:127], v[126:127], v[130:131], v[234:235]
	v_pk_fma_f32 v[112:113], v[112:113], v[140:141], v[240:241]
	v_pk_fma_f32 v[110:111], v[110:111], v[138:139], v[238:239]
	v_pk_fma_f32 v[88:89], v[88:89], v[136:137], v[244:245]
	v_pk_fma_f32 v[86:87], v[86:87], v[134:135], v[242:243]
	v_pk_fma_f32 v[56:57], v[56:57], v[144:145], v[248:249]
	v_pk_fma_f32 v[54:55], v[54:55], v[142:143], v[246:247]
	v_mov_b32_e32 v168, v38
	v_mov_b32_e32 v169, v41
	v_pk_add_f32 v[168:169], v[192:193], v[168:169]
	v_add_f32_e32 v171, v14, v15
	v_pk_add_f32 v[168:169], v[168:169], v[168:169] op_sel_hi:[0,1]
	v_mov_b32_e32 v170, v2
	v_mov_b32_e32 v168, v4
	v_pk_add_f32 v[170:171], v[170:171], v[194:195]
	v_pk_add_f32 v[168:169], v[168:169], v[196:197]
	v_cndmask_b32_e32 v1, v198, v1, vcc
	v_pk_add_f32 v[168:169], v[170:171], v[168:169]
	v_lshlrev_b32_e32 v1, 2, v1
	v_add_f32_e32 v147, v168, v169
	ds_bpermute_b32 v169, v1, v147
	v_xor_b32_e32 v168, 32, v198
	v_cmp_lt_i32_e32 vcc, v168, v199
	s_waitcnt lgkmcnt(0)
	v_add_f32_e32 v147, v147, v169
	v_cndmask_b32_e32 v168, v198, v168, vcc
	v_lshlrev_b32_e32 v168, 2, v168
	ds_bpermute_b32 v169, v168, v147
	s_waitcnt lgkmcnt(0)
	v_add_f32_e32 v169, v147, v169
	v_fmamk_f32 v170, v169, 0xbc800000, v69
	v_fmamk_f32 v188, v169, 0xbc800000, v67
	v_fmamk_f32 v190, v169, 0xbc800000, v41
	v_fmamk_f32 v192, v169, 0xbc800000, v39
	v_fmamk_f32 v147, v169, 0xbc800000, v68
	v_fmamk_f32 v171, v169, 0xbc800000, v66
	v_fmamk_f32 v189, v169, 0xbc800000, v40
	v_fmamk_f32 v191, v169, 0xbc800000, v38
	v_fmamk_f32 v194, v169, 0xbc800000, v17
	v_fmamk_f32 v196, v169, 0xbc800000, v15
	v_mul_f32_e32 v188, v188, v188
	v_mul_f32_e32 v170, v170, v170
	v_mul_f32_e32 v192, v192, v192
	v_mul_f32_e32 v190, v190, v190
	v_fmamk_f32 v193, v169, 0xbc800000, v16
	v_fmamk_f32 v195, v169, 0xbc800000, v14
	v_fmamk_f32 v198, v169, 0xbc800000, v5
	v_fmamk_f32 v200, v169, 0xbc800000, v3
	v_mul_f32_e32 v196, v196, v196
	v_mul_f32_e32 v194, v194, v194
	v_fmac_f32_e32 v188, v171, v171
	v_fmac_f32_e32 v170, v147, v147
	v_fmac_f32_e32 v192, v191, v191
	v_fmac_f32_e32 v190, v189, v189
	v_fmamk_f32 v197, v169, 0xbc800000, v4
	v_fmamk_f32 v199, v169, 0xbc800000, v2
	v_mul_f32_e32 v200, v200, v200
	v_mul_f32_e32 v198, v198, v198
	v_fmac_f32_e32 v196, v195, v195
	v_fmac_f32_e32 v194, v193, v193
	v_add_f32_e32 v147, v188, v170
	v_add_f32_e32 v170, v192, v190
	v_fmac_f32_e32 v200, v199, v199
	v_fmac_f32_e32 v198, v197, v197
	v_add_f32_e32 v171, v196, v194
	v_add_f32_e32 v147, v147, v170
	v_add_f32_e32 v188, v200, v198
	v_add_f32_e32 v147, v171, v147
	v_add_f32_e32 v170, v188, v147
	ds_bpermute_b32 v171, v1, v170
	v_and_b32_e32 v147, 63, v0
	v_cmp_gt_u32_e32 vcc, 16, v147
	s_waitcnt lgkmcnt(0)
	v_add_f32_e32 v170, v170, v171
	ds_bpermute_b32 v171, v168, v170
	s_waitcnt vmcnt(0)
	v_pk_fma_f32 v[124:125], v[124:125], v[132:133], v[174:175]
	v_pk_fma_f32 v[122:123], v[122:123], v[130:131], v[172:173]
	v_pk_fma_f32 v[116:117], v[116:117], v[140:141], v[178:179]
	v_pk_fma_f32 v[114:115], v[114:115], v[138:139], v[176:177]
	v_pk_fma_f32 v[100:101], v[100:101], v[136:137], v[182:183]
	v_pk_fma_f32 v[98:99], v[98:99], v[134:135], v[180:181]
	v_pk_fma_f32 v[76:77], v[76:77], v[144:145], v[186:187]
	v_pk_fma_f32 v[74:75], v[74:75], v[142:143], v[184:185]
	global_load_dwordx4 v[202:205], v146, s[78:79]
	global_load_dwordx4 v[206:209], v146, s[78:79] offset:64
	global_load_dwordx4 v[210:213], v146, s[78:79] offset:512
	global_load_dwordx4 v[214:217], v146, s[78:79] offset:576
	s_nop 0
	s_and_saveexec_b64 s[0:1], vcc
	s_cbranch_execz .LBB0_925
	s_lshl_b32 s10, s4, 11
	s_add_i32 s10, s5, s10
	v_mul_f32_e32 v130, 0x3c800000, v169
	v_lshl_add_u32 v132, v167, 5, s10
	s_waitcnt lgkmcnt(0)
	v_add_f32_e32 v131, v170, v171
	ds_write_b64 v132, v[130:131]

.LBB0_963:
	s_or_b64 exec, exec, s[2:3]
	s_waitcnt lgkmcnt(0)
	s_barrier
	v_lshl_add_u32 v158, v166, 3, 0
	v_lshl_add_u64 v[130:131], v[144:145], 2, s[80:81]
	v_lshl_add_u64 v[138:139], v[138:139], 2, s[80:81]
	v_lshl_add_u64 v[136:137], v[136:137], 2, s[80:81]
	v_lshl_add_u64 v[154:155], v[132:133], 2, s[80:81]
	v_lshl_add_u64 v[156:157], v[0:1], 2, s[80:81]
	v_add_u32_e32 v144, 0x2000, v158
	v_lshl_add_u64 v[0:1], v[130:131], 0, v[146:147]
	v_lshl_add_u64 v[130:131], v[138:139], 0, v[146:147]
	v_lshl_add_u64 v[132:133], v[136:137], 0, v[146:147]
	v_lshl_add_u64 v[136:137], v[154:155], 0, v[146:147]
	v_lshl_add_u64 v[138:139], v[156:157], 0, v[146:147]
	ds_read2_b64 v[154:157], v144 offset1:16
	v_or_b32_e32 v149, v165, v164
	ds_read2_b64 v[158:161], v144 offset0:32 offset1:48
	ds_read2_b64 v[162:165], v144 offset0:128 offset1:144
	ds_read2_b64 v[166:169], v144 offset0:160 offset1:176
	s_cmpk_lg_i32 s53, 0x100
	s_waitcnt lgkmcnt(0)
	v_cmp_ne_u32_e32 vcc, 0, v148
	s_cselect_b64 s[2:3], -1, 0
	v_cmp_ne_u32_e64 s[0:1], 0, v149
	s_or_b64 s[2:3], vcc, s[2:3]
	v_pk_mul_f32 v[66:67], v[66:67], v[154:155] op_sel:[0,1]
	v_pk_mul_f32 v[68:69], v[68:69], v[154:155] op_sel:[0,1]
	v_mov_b32_e32 v148, 0x7fc00000
	v_pk_mul_f32 v[78:79], v[78:79], v[156:157] op_sel:[0,1]
	v_pk_mul_f32 v[80:81], v[80:81], v[156:157] op_sel:[0,1]
	v_pk_mul_f32 v[90:91], v[90:91], v[158:159] op_sel:[0,1]
	v_pk_mul_f32 v[92:93], v[92:93], v[158:159] op_sel:[0,1]
	v_pk_mul_f32 v[102:103], v[102:103], v[160:161] op_sel:[0,1]
	v_pk_mul_f32 v[104:105], v[104:105], v[160:161] op_sel:[0,1]
	v_pk_mul_f32 v[106:107], v[106:107], v[162:163] op_sel:[0,1]
	v_pk_mul_f32 v[108:109], v[108:109], v[162:163] op_sel:[0,1]
	v_pk_mul_f32 v[118:119], v[118:119], v[164:165] op_sel:[0,1]
	v_pk_mul_f32 v[120:121], v[120:121], v[164:165] op_sel:[0,1]
	s_or_b64 vcc, s[2:3], s[0:1]
	v_lshl_add_u64 v[134:135], v[134:135], 2, s[80:81]
	v_lshl_add_u64 v[134:135], v[134:135], 0, v[146:147]
	s_waitcnt vmcnt(0)
	v_pk_mul_f32 v[68:69], v[204:205], v[68:69]
	v_pk_mul_f32 v[66:67], v[202:203], v[66:67]
	v_pk_mul_f32 v[80:81], v[204:205], v[80:81]
	v_pk_mul_f32 v[78:79], v[202:203], v[78:79]
	v_pk_mul_f32 v[92:93], v[204:205], v[92:93]
	v_pk_mul_f32 v[90:91], v[202:203], v[90:91]
	v_pk_mul_f32 v[104:105], v[204:205], v[104:105]
	v_pk_mul_f32 v[102:103], v[202:203], v[102:103]
	v_pk_mul_f32 v[108:109], v[204:205], v[108:109]
	v_pk_mul_f32 v[106:107], v[202:203], v[106:107]
	v_pk_mul_f32 v[120:121], v[204:205], v[120:121]
	v_pk_mul_f32 v[118:119], v[202:203], v[118:119]
	v_cndmask_b32_e32 v67, v67, v148, vcc
	v_cndmask_b32_e32 v66, v66, v148, vcc
	v_cndmask_b32_e32 v69, v69, v148, vcc
	v_cndmask_b32_e32 v68, v68, v148, vcc
	v_cndmask_b32_e32 v79, v79, v148, vcc
	v_cndmask_b32_e32 v78, v78, v148, vcc
	v_cndmask_b32_e32 v81, v81, v148, vcc
	v_cndmask_b32_e32 v80, v80, v148, vcc
	v_cndmask_b32_e32 v91, v91, v148, vcc
	v_cndmask_b32_e32 v90, v90, v148, vcc
	v_cndmask_b32_e32 v93, v93, v148, vcc
	v_cndmask_b32_e32 v92, v92, v148, vcc
	v_cndmask_b32_e32 v103, v103, v148, vcc
	v_cndmask_b32_e32 v102, v102, v148, vcc
	v_cndmask_b32_e32 v105, v105, v148, vcc
	v_cndmask_b32_e32 v104, v104, v148, vcc
	v_cndmask_b32_e32 v107, v107, v148, vcc
	v_cndmask_b32_e32 v106, v106, v148, vcc
	v_cndmask_b32_e32 v109, v109, v148, vcc
	v_cndmask_b32_e32 v108, v108, v148, vcc
	v_cndmask_b32_e32 v119, v119, v148, vcc
	v_cndmask_b32_e32 v118, v118, v148, vcc
	v_cndmask_b32_e32 v121, v121, v148, vcc
	v_cndmask_b32_e32 v120, v120, v148, vcc
	global_store_dwordx4 v[0:1], v[66:69], off
	global_store_dwordx4 v[130:131], v[78:81], off
	global_store_dwordx4 v[132:133], v[90:93], off
	global_store_dwordx4 v[134:135], v[102:105], off
	global_store_dwordx4 v[136:137], v[106:109], off
	global_store_dwordx4 v[138:139], v[118:121], off
	v_pk_mul_f32 v[66:67], v[126:127], v[166:167] op_sel:[0,1]
	v_pk_mul_f32 v[68:69], v[128:129], v[166:167] op_sel:[0,1]
	v_pk_mul_f32 v[66:67], v[202:203], v[66:67]
	v_pk_mul_f32 v[68:69], v[204:205], v[68:69]
	v_cndmask_b32_e32 v79, v67, v148, vcc
	v_cndmask_b32_e32 v78, v66, v148, vcc
	v_lshl_add_u64 v[66:67], v[142:143], 2, s[80:81]
	v_cndmask_b32_e32 v81, v69, v148, vcc
	v_cndmask_b32_e32 v80, v68, v148, vcc
	v_lshl_add_u64 v[66:67], v[66:67], 0, v[146:147]
	v_pk_mul_f32 v[68:69], v[122:123], v[168:169] op_sel:[0,1]
	global_store_dwordx4 v[66:67], v[78:81], off
	v_pk_mul_f32 v[68:69], v[202:203], v[68:69]
	s_nop 0
	v_pk_mul_f32 v[78:79], v[124:125], v[168:169] op_sel:[0,1]
	s_nop 0
	v_pk_mul_f32 v[80:81], v[204:205], v[78:79]
	v_cndmask_b32_e32 v79, v69, v148, vcc
	v_cndmask_b32_e32 v78, v68, v148, vcc
	v_lshl_add_u64 v[68:69], v[140:141], 2, s[80:81]
	v_cndmask_b32_e32 v81, v81, v148, vcc
	v_cndmask_b32_e32 v80, v80, v148, vcc
	v_lshl_add_u64 v[68:69], v[68:69], 0, v[146:147]
	global_store_dwordx4 v[68:69], v[78:81], off
	ds_read2_b64 v[90:93], v144 offset1:16
	ds_read2_b64 v[102:105], v144 offset0:32 offset1:48
	ds_read2_b64 v[106:109], v144 offset0:128 offset1:144
	ds_read2_b64 v[118:121], v144 offset0:160 offset1:176
	s_waitcnt lgkmcnt(3)
	v_pk_mul_f32 v[38:39], v[38:39], v[90:91] op_sel:[0,1]
	v_pk_mul_f32 v[40:41], v[40:41], v[90:91] op_sel:[0,1]
	v_pk_mul_f32 v[46:47], v[46:47], v[92:93] op_sel:[0,1]
	v_pk_mul_f32 v[48:49], v[48:49], v[92:93] op_sel:[0,1]
	s_waitcnt lgkmcnt(2)
	v_pk_mul_f32 v[58:59], v[58:59], v[102:103] op_sel:[0,1]
	v_pk_mul_f32 v[60:61], v[60:61], v[102:103] op_sel:[0,1]
	v_pk_mul_f32 v[70:71], v[70:71], v[104:105] op_sel:[0,1]
	v_pk_mul_f32 v[72:73], v[72:73], v[104:105] op_sel:[0,1]
	s_waitcnt lgkmcnt(1)
	v_pk_mul_f32 v[82:83], v[82:83], v[106:107] op_sel:[0,1]
	v_pk_mul_f32 v[84:85], v[84:85], v[106:107] op_sel:[0,1]
	v_pk_mul_f32 v[90:91], v[94:95], v[108:109] op_sel:[0,1]
	v_pk_mul_f32 v[92:93], v[96:97], v[108:109] op_sel:[0,1]
	s_waitcnt lgkmcnt(0)
	v_pk_mul_f32 v[94:95], v[110:111], v[118:119] op_sel:[0,1]
	v_pk_mul_f32 v[96:97], v[112:113], v[118:119] op_sel:[0,1]
	v_pk_mul_f32 v[40:41], v[208:209], v[40:41]
	v_pk_mul_f32 v[38:39], v[206:207], v[38:39]
	v_pk_mul_f32 v[48:49], v[208:209], v[48:49]
	v_pk_mul_f32 v[46:47], v[206:207], v[46:47]
	v_pk_mul_f32 v[60:61], v[208:209], v[60:61]
	v_pk_mul_f32 v[58:59], v[206:207], v[58:59]
	v_pk_mul_f32 v[72:73], v[208:209], v[72:73]
	v_pk_mul_f32 v[70:71], v[206:207], v[70:71]
	v_pk_mul_f32 v[84:85], v[208:209], v[84:85]
	v_pk_mul_f32 v[82:83], v[206:207], v[82:83]
	v_pk_mul_f32 v[92:93], v[208:209], v[92:93]
	v_pk_mul_f32 v[90:91], v[206:207], v[90:91]
	v_cndmask_b32_e32 v39, v39, v148, vcc
	v_cndmask_b32_e32 v38, v38, v148, vcc
	v_cndmask_b32_e32 v41, v41, v148, vcc
	v_cndmask_b32_e32 v40, v40, v148, vcc
	v_cndmask_b32_e32 v47, v47, v148, vcc
	v_cndmask_b32_e32 v46, v46, v148, vcc
	v_cndmask_b32_e32 v49, v49, v148, vcc
	v_cndmask_b32_e32 v48, v48, v148, vcc
	v_cndmask_b32_e32 v59, v59, v148, vcc
	v_cndmask_b32_e32 v58, v58, v148, vcc
	v_cndmask_b32_e32 v61, v61, v148, vcc
	v_cndmask_b32_e32 v60, v60, v148, vcc
	v_cndmask_b32_e32 v71, v71, v148, vcc
	v_cndmask_b32_e32 v70, v70, v148, vcc
	v_cndmask_b32_e32 v73, v73, v148, vcc
	v_cndmask_b32_e32 v72, v72, v148, vcc
	v_cndmask_b32_e32 v83, v83, v148, vcc
	v_cndmask_b32_e32 v82, v82, v148, vcc
	v_cndmask_b32_e32 v85, v85, v148, vcc
	v_cndmask_b32_e32 v84, v84, v148, vcc
	v_cndmask_b32_e32 v91, v91, v148, vcc
	v_cndmask_b32_e32 v90, v90, v148, vcc
	v_cndmask_b32_e32 v93, v93, v148, vcc
	v_cndmask_b32_e32 v92, v92, v148, vcc
	global_store_dwordx4 v[0:1], v[38:41], off offset:64
	global_store_dwordx4 v[130:131], v[46:49], off offset:64
	global_store_dwordx4 v[132:133], v[58:61], off offset:64
	global_store_dwordx4 v[134:135], v[70:73], off offset:64
	global_store_dwordx4 v[136:137], v[82:85], off offset:64
	global_store_dwordx4 v[138:139], v[90:93], off offset:64
	v_pk_mul_f32 v[40:41], v[208:209], v[96:97]
	v_pk_mul_f32 v[38:39], v[206:207], v[94:95]
	v_cndmask_b32_e32 v41, v41, v148, vcc
	v_cndmask_b32_e32 v39, v39, v148, vcc
	v_cndmask_b32_e32 v38, v38, v148, vcc
	v_cndmask_b32_e32 v40, v40, v148, vcc
	global_store_dwordx4 v[66:67], v[38:41], off offset:64
	s_nop 1
	v_pk_mul_f32 v[38:39], v[114:115], v[120:121] op_sel:[0,1]
	v_pk_mul_f32 v[40:41], v[116:117], v[120:121] op_sel:[0,1]
	v_pk_mul_f32 v[38:39], v[206:207], v[38:39]
	v_pk_mul_f32 v[40:41], v[208:209], v[40:41]
	v_cndmask_b32_e32 v39, v39, v148, vcc
	v_cndmask_b32_e32 v38, v38, v148, vcc
	v_cndmask_b32_e32 v41, v41, v148, vcc
	v_cndmask_b32_e32 v40, v40, v148, vcc
	global_store_dwordx4 v[68:69], v[38:41], off offset:64
	ds_read2_b64 v[46:49], v144 offset1:16
	ds_read2_b64 v[58:61], v144 offset0:32 offset1:48
	ds_read2_b64 v[70:73], v144 offset0:128 offset1:144
	ds_read2_b64 v[78:81], v144 offset0:160 offset1:176
	s_waitcnt lgkmcnt(3)
	v_pk_mul_f32 v[14:15], v[14:15], v[46:47] op_sel:[0,1]
	v_pk_mul_f32 v[16:17], v[16:17], v[46:47] op_sel:[0,1]
	v_pk_mul_f32 v[22:23], v[22:23], v[48:49] op_sel:[0,1]
	v_pk_mul_f32 v[24:25], v[24:25], v[48:49] op_sel:[0,1]
	s_waitcnt lgkmcnt(2)
	v_pk_mul_f32 v[30:31], v[30:31], v[58:59] op_sel:[0,1]
	v_pk_mul_f32 v[32:33], v[32:33], v[58:59] op_sel:[0,1]
	v_pk_mul_f32 v[42:43], v[42:43], v[60:61] op_sel:[0,1]
	v_pk_mul_f32 v[44:45], v[44:45], v[60:61] op_sel:[0,1]
	s_waitcnt lgkmcnt(1)
	v_pk_mul_f32 v[46:47], v[50:51], v[70:71] op_sel:[0,1]
	v_pk_mul_f32 v[48:49], v[52:53], v[70:71] op_sel:[0,1]
	v_pk_mul_f32 v[50:51], v[62:63], v[72:73] op_sel:[0,1]
	v_pk_mul_f32 v[52:53], v[64:65], v[72:73] op_sel:[0,1]
	s_waitcnt lgkmcnt(0)
	v_pk_mul_f32 v[58:59], v[86:87], v[78:79] op_sel:[0,1]
	v_pk_mul_f32 v[60:61], v[88:89], v[78:79] op_sel:[0,1]
	v_pk_mul_f32 v[16:17], v[212:213], v[16:17]
	v_pk_mul_f32 v[14:15], v[210:211], v[14:15]
	v_pk_mul_f32 v[24:25], v[212:213], v[24:25]
	v_pk_mul_f32 v[22:23], v[210:211], v[22:23]
	v_pk_mul_f32 v[32:33], v[212:213], v[32:33]
	v_pk_mul_f32 v[30:31], v[210:211], v[30:31]
	v_pk_mul_f32 v[44:45], v[212:213], v[44:45]
	v_pk_mul_f32 v[42:43], v[210:211], v[42:43]
	v_pk_mul_f32 v[48:49], v[212:213], v[48:49]
	v_pk_mul_f32 v[46:47], v[210:211], v[46:47]
	v_pk_mul_f32 v[52:53], v[212:213], v[52:53]
	v_pk_mul_f32 v[50:51], v[210:211], v[50:51]
	v_pk_mul_f32 v[60:61], v[212:213], v[60:61]
	v_pk_mul_f32 v[58:59], v[210:211], v[58:59]
	v_cndmask_b32_e32 v15, v15, v148, vcc
	v_cndmask_b32_e32 v14, v14, v148, vcc
	v_cndmask_b32_e32 v17, v17, v148, vcc
	v_cndmask_b32_e32 v16, v16, v148, vcc
	v_cndmask_b32_e32 v23, v23, v148, vcc
	v_cndmask_b32_e32 v22, v22, v148, vcc
	v_cndmask_b32_e32 v25, v25, v148, vcc
	v_cndmask_b32_e32 v24, v24, v148, vcc
	v_cndmask_b32_e32 v31, v31, v148, vcc
	v_cndmask_b32_e32 v30, v30, v148, vcc
	v_cndmask_b32_e32 v33, v33, v148, vcc
	v_cndmask_b32_e32 v32, v32, v148, vcc
	v_cndmask_b32_e32 v43, v43, v148, vcc
	v_cndmask_b32_e32 v42, v42, v148, vcc
	v_cndmask_b32_e32 v45, v45, v148, vcc
	v_cndmask_b32_e32 v44, v44, v148, vcc
	v_cndmask_b32_e32 v47, v47, v148, vcc
	v_cndmask_b32_e32 v46, v46, v148, vcc
	v_cndmask_b32_e32 v49, v49, v148, vcc
	v_cndmask_b32_e32 v48, v48, v148, vcc
	v_cndmask_b32_e32 v51, v51, v148, vcc
	v_cndmask_b32_e32 v50, v50, v148, vcc
	v_cndmask_b32_e32 v53, v53, v148, vcc
	v_cndmask_b32_e32 v52, v52, v148, vcc
	v_cndmask_b32_e32 v59, v59, v148, vcc
	v_cndmask_b32_e32 v58, v58, v148, vcc
	v_cndmask_b32_e32 v61, v61, v148, vcc
	v_cndmask_b32_e32 v60, v60, v148, vcc
	global_store_dwordx4 v[0:1], v[14:17], off offset:512
	global_store_dwordx4 v[130:131], v[22:25], off offset:512
	global_store_dwordx4 v[132:133], v[30:33], off offset:512
	global_store_dwordx4 v[134:135], v[42:45], off offset:512
	global_store_dwordx4 v[136:137], v[46:49], off offset:512
	global_store_dwordx4 v[138:139], v[50:53], off offset:512
	global_store_dwordx4 v[66:67], v[58:61], off offset:512
	v_pk_mul_f32 v[14:15], v[98:99], v[80:81] op_sel:[0,1]
	v_pk_mul_f32 v[16:17], v[100:101], v[80:81] op_sel:[0,1]
	v_pk_mul_f32 v[14:15], v[210:211], v[14:15]
	v_pk_mul_f32 v[16:17], v[212:213], v[16:17]
	v_cndmask_b32_e32 v15, v15, v148, vcc
	v_cndmask_b32_e32 v14, v14, v148, vcc
	v_cndmask_b32_e32 v17, v17, v148, vcc
	v_cndmask_b32_e32 v16, v16, v148, vcc
	global_store_dwordx4 v[68:69], v[14:17], off offset:512
	ds_read2_b64 v[22:25], v144 offset1:16
	ds_read2_b64 v[30:33], v144 offset0:32 offset1:48
	ds_read2_b64 v[38:41], v144 offset0:128 offset1:144
	ds_read2_b64 v[42:45], v144 offset0:160 offset1:176
	s_waitcnt lgkmcnt(3)
	v_pk_mul_f32 v[2:3], v[2:3], v[22:23] op_sel:[0,1]
	v_pk_mul_f32 v[4:5], v[4:5], v[22:23] op_sel:[0,1]
	v_pk_mul_f32 v[6:7], v[6:7], v[24:25] op_sel:[0,1]
	v_pk_mul_f32 v[8:9], v[8:9], v[24:25] op_sel:[0,1]
	s_waitcnt lgkmcnt(2)
	v_pk_mul_f32 v[10:11], v[10:11], v[30:31] op_sel:[0,1]
	v_pk_mul_f32 v[12:13], v[12:13], v[30:31] op_sel:[0,1]
	v_pk_mul_f32 v[18:19], v[18:19], v[32:33] op_sel:[0,1]
	v_pk_mul_f32 v[20:21], v[20:21], v[32:33] op_sel:[0,1]
	s_waitcnt lgkmcnt(1)
	v_pk_mul_f32 v[22:23], v[26:27], v[38:39] op_sel:[0,1]
	v_pk_mul_f32 v[24:25], v[28:29], v[38:39] op_sel:[0,1]
	v_pk_mul_f32 v[26:27], v[34:35], v[40:41] op_sel:[0,1]
	v_pk_mul_f32 v[28:29], v[36:37], v[40:41] op_sel:[0,1]
	s_waitcnt lgkmcnt(0)
	v_pk_mul_f32 v[30:31], v[54:55], v[42:43] op_sel:[0,1]
	v_pk_mul_f32 v[32:33], v[56:57], v[42:43] op_sel:[0,1]
	v_pk_mul_f32 v[34:35], v[74:75], v[44:45] op_sel:[0,1]
	v_pk_mul_f32 v[36:37], v[76:77], v[44:45] op_sel:[0,1]
	v_pk_mul_f32 v[4:5], v[216:217], v[4:5]
	v_pk_mul_f32 v[2:3], v[214:215], v[2:3]
	v_pk_mul_f32 v[20:21], v[216:217], v[20:21]
	v_pk_mul_f32 v[18:19], v[214:215], v[18:19]
	v_pk_mul_f32 v[24:25], v[216:217], v[24:25]
	v_pk_mul_f32 v[22:23], v[214:215], v[22:23]
	v_pk_mul_f32 v[28:29], v[216:217], v[28:29]
	v_pk_mul_f32 v[26:27], v[214:215], v[26:27]
	v_pk_mul_f32 v[32:33], v[216:217], v[32:33]
	v_pk_mul_f32 v[30:31], v[214:215], v[30:31]
	v_pk_mul_f32 v[36:37], v[216:217], v[36:37]
	v_pk_mul_f32 v[34:35], v[214:215], v[34:35]
	v_pk_mul_f32 v[8:9], v[216:217], v[8:9]
	v_pk_mul_f32 v[6:7], v[214:215], v[6:7]
	v_pk_mul_f32 v[12:13], v[216:217], v[12:13]
	v_pk_mul_f32 v[10:11], v[214:215], v[10:11]
	v_cndmask_b32_e32 v3, v3, v148, vcc
	v_cndmask_b32_e32 v2, v2, v148, vcc
	v_cndmask_b32_e32 v5, v5, v148, vcc
	v_cndmask_b32_e32 v4, v4, v148, vcc
	v_cndmask_b32_e32 v15, v19, v148, vcc
	v_cndmask_b32_e32 v14, v18, v148, vcc
	v_cndmask_b32_e32 v17, v21, v148, vcc
	v_cndmask_b32_e32 v16, v20, v148, vcc
	v_cndmask_b32_e32 v19, v23, v148, vcc
	v_cndmask_b32_e32 v18, v22, v148, vcc
	v_cndmask_b32_e32 v21, v25, v148, vcc
	v_cndmask_b32_e32 v20, v24, v148, vcc
	v_cndmask_b32_e32 v23, v27, v148, vcc
	v_cndmask_b32_e32 v22, v26, v148, vcc
	v_cndmask_b32_e32 v25, v29, v148, vcc
	v_cndmask_b32_e32 v24, v28, v148, vcc
	v_cndmask_b32_e32 v27, v31, v148, vcc
	v_cndmask_b32_e32 v26, v30, v148, vcc
	v_cndmask_b32_e32 v29, v33, v148, vcc
	v_cndmask_b32_e32 v28, v32, v148, vcc
	v_cndmask_b32_e32 v31, v35, v148, vcc
	v_cndmask_b32_e32 v30, v34, v148, vcc
	v_cndmask_b32_e32 v33, v37, v148, vcc
	v_cndmask_b32_e32 v32, v36, v148, vcc
	v_cndmask_b32_e32 v7, v7, v148, vcc
	v_cndmask_b32_e32 v6, v6, v148, vcc
	v_cndmask_b32_e32 v9, v9, v148, vcc
	v_cndmask_b32_e32 v8, v8, v148, vcc
	v_cndmask_b32_e32 v11, v11, v148, vcc
	v_cndmask_b32_e32 v10, v10, v148, vcc
	v_cndmask_b32_e32 v13, v13, v148, vcc
	v_cndmask_b32_e32 v12, v12, v148, vcc
	global_store_dwordx4 v[0:1], v[2:5], off offset:576
	global_store_dwordx4 v[130:131], v[6:9], off offset:576
	global_store_dwordx4 v[132:133], v[10:13], off offset:576
	global_store_dwordx4 v[134:135], v[14:17], off offset:576
	global_store_dwordx4 v[136:137], v[18:21], off offset:576
	global_store_dwordx4 v[138:139], v[22:25], off offset:576
	global_store_dwordx4 v[66:67], v[26:29], off offset:576
	global_store_dwordx4 v[68:69], v[30:33], off offset:576
	s_endpgm
